# XCD barrier leader poll: 16 counter loads issued back to back behind one vmcnt(0) (was one full wait per load), on top of v31
# baseline (speedup 1.0000x reference)
; __device__ __forceinline__ unsigned xb_ld(unsigned* p)              { return __hip_atomic_load(p, __ATOMIC_RELAXED, __HIP_MEMORY_SCOPE_AGENT); }
; __device__ __forceinline__ void xcd_barrier_complete(unsigned* bar, unsigned x, unsigned& nloc, unsigned& nx) {
;     const unsigned G = gridDim.x * gridDim.y * gridDim.z;
;     unsigned sum, cnt, mine, sp = 0u;
;     for (;;) {
;         sum = 0u; cnt = 0u; mine = 0u;
; #pragma unroll
;         for (unsigned j = 0; j < 16; ++j) { const unsigned c = xb_ld(&bar[XB_XCNT(j)]); sum += c; cnt += (c > 0u) ? 1u : 0u; mine = (j == x) ? c : mine; }
;         if (sum == G) break;
;         __builtin_amdgcn_s_sleep(1);
;         if ((++sp & 255u) == 0u) { if (xb_ld(&bar[XB_TMO])) break; if (sp > XB_SPIN_CAP) { atomicAdd(&bar[XB_TMO], 1u); break; } }
;     }
.LBB0_1133:
	v_readlane_b32 s2, v253, 11
	v_readlane_b32 s3, v253, 12
	s_mov_b64 s[8:9], -1
	s_nop 3
	global_load_dword v1, v0, s[2:3] sc1
	v_readlane_b32 s2, v253, 13
	v_readlane_b32 s3, v253, 14
	s_waitcnt lgkmcnt(0)
	s_nop 4
	global_load_dword v2, v0, s[2:3] sc1
	v_readlane_b32 s2, v253, 15
	v_readlane_b32 s3, v253, 16
	s_nop 4
	global_load_dword v3, v0, s[2:3] sc1
	v_readlane_b32 s2, v253, 17
	v_readlane_b32 s3, v253, 18
	s_nop 4
	global_load_dword v4, v0, s[2:3] sc1
	v_readlane_b32 s2, v253, 19
	v_readlane_b32 s3, v253, 20
	s_nop 4
	global_load_dword v5, v0, s[2:3] sc1
	v_readlane_b32 s2, v253, 21
	v_readlane_b32 s3, v253, 22
	s_nop 4
	global_load_dword v6, v0, s[2:3] sc1
	v_readlane_b32 s2, v253, 23
	v_readlane_b32 s3, v253, 24
	s_nop 4
	global_load_dword v7, v0, s[2:3] sc1
	v_readlane_b32 s2, v253, 25
	v_readlane_b32 s3, v253, 26
	s_nop 4
	global_load_dword v8, v0, s[2:3] sc1
	v_readlane_b32 s2, v253, 27
	v_readlane_b32 s3, v253, 28
	s_nop 4
	global_load_dword v9, v0, s[2:3] sc1
	v_readlane_b32 s2, v253, 29
	v_readlane_b32 s3, v253, 30
	s_nop 4
	global_load_dword v10, v0, s[2:3] sc1
	v_readlane_b32 s2, v253, 31
	v_readlane_b32 s3, v253, 32
	s_nop 4
	global_load_dword v11, v0, s[2:3] sc1
	v_readlane_b32 s2, v253, 33
	v_readlane_b32 s3, v253, 34
	s_nop 4
	global_load_dword v12, v0, s[2:3] sc1
	v_readlane_b32 s2, v253, 35
	v_readlane_b32 s3, v253, 36
	s_nop 4
	global_load_dword v13, v0, s[2:3] sc1
	v_readlane_b32 s2, v253, 37
	v_readlane_b32 s3, v253, 38
	s_nop 4
	global_load_dword v14, v0, s[2:3] sc1
	v_readlane_b32 s2, v253, 39
	v_readlane_b32 s3, v253, 40
	s_nop 4
	global_load_dword v15, v0, s[2:3] sc1
	v_readlane_b32 s2, v253, 41
	v_readlane_b32 s3, v253, 42
	s_nop 4
	global_load_dword v16, v0, s[2:3] sc1
	s_mov_b64 s[2:3], -1
	s_waitcnt vmcnt(0)
	v_add_u32_e32 v17, v2, v1
	v_add_u32_e32 v17, v17, v3
	v_add_u32_e32 v17, v17, v4
	v_add_u32_e32 v17, v17, v5
	v_add_u32_e32 v17, v17, v6
	v_add_u32_e32 v17, v17, v7
	v_add_u32_e32 v17, v17, v8
	v_add_u32_e32 v17, v17, v9
	v_add_u32_e32 v17, v17, v10
	v_add_u32_e32 v17, v17, v11
	v_add_u32_e32 v17, v17, v12
	v_add_u32_e32 v17, v17, v13
	v_add_u32_e32 v17, v17, v14
	v_add_u32_e32 v17, v17, v15
	v_add_u32_e32 v17, v17, v16
	v_cmp_eq_u32_e32 vcc, s19, v17
	s_cbranch_vccnz .LBB0_1132
	s_and_b32 s2, s12, 0xff
	s_cmp_eq_u32 s2, 0
	s_mov_b64 s[2:3], -1
	s_mov_b64 s[10:11], -1
	s_sleep 1
	s_cbranch_scc1 .LBB0_1137
	s_and_b64 vcc, exec, s[10:11]
	s_cbranch_vccz .LBB0_1132
